# MLA attention: steady-state common path falls through, rare rescale block moved out of line
# baseline (speedup 1.0000x reference)
.LBB0_288:
	v_cmp_lt_f32_e32 vcc, s16, v83
	s_cbranch_vccnz .Lresc_mA
.Lmla_A0:
	ds_read_b128 v[84:87], v254 offset:12288
	ds_read_b128 v[88:91], v254 offset:12800
	s_and_b64 vcc, exec, s[8:9]
	s_waitcnt vmcnt(1)
	ds_write_b128 v228, v[174:177]
	s_cbranch_vccnz .LBB0_293

.Lresc_mA:
	ds_bpermute_b32 v34, v251, v83
	s_waitcnt lgkmcnt(0)
	v_max3_f32 v35, v83, v34, 0
	v_exp_f32_e64 v34, -v35
	s_and_saveexec_b64 s[12:13], s[6:7]
	ds_write_b32 v209, v34 offset:57344
	s_or_b64 exec, exec, s[12:13]
	ds_read_b128 v[36:39], v207 offset:57408
	ds_read_b128 v[40:43], v207 offset:57440
	ds_read_b128 v[44:47], v207 offset:57344
	ds_read_b128 v[84:87], v207 offset:57376
	v_add_f32_e32 v229, v229, v35
	v_xor_b32_e32 v82, 0x80000000, v229
	v_mov_b32_e32 v83, v82
	v_sub_f32_e32 v65, v65, v35
	v_sub_f32_e32 v64, v64, v35
	v_sub_f32_e32 v63, v63, v35
	v_sub_f32_e32 v62, v62, v35
	v_sub_f32_e32 v61, v61, v35
	v_sub_f32_e32 v60, v60, v35
	v_sub_f32_e32 v59, v59, v35
	v_sub_f32_e32 v58, v58, v35
	v_sub_f32_e32 v57, v57, v35
	v_sub_f32_e32 v56, v56, v35
	v_sub_f32_e32 v55, v55, v35
	v_sub_f32_e32 v54, v54, v35
	v_sub_f32_e32 v53, v53, v35
	v_sub_f32_e32 v52, v52, v35
	v_sub_f32_e32 v51, v51, v35
	v_sub_f32_e32 v50, v50, v35
	v_sub_f32_e32 v81, v81, v35
	v_sub_f32_e32 v80, v80, v35
	v_sub_f32_e32 v79, v79, v35
	v_sub_f32_e32 v78, v78, v35
	v_sub_f32_e32 v77, v77, v35
	v_sub_f32_e32 v76, v76, v35
	v_sub_f32_e32 v75, v75, v35
	v_sub_f32_e32 v74, v74, v35
	v_sub_f32_e32 v73, v73, v35
	v_sub_f32_e32 v72, v72, v35
	v_sub_f32_e32 v71, v71, v35
	v_sub_f32_e32 v70, v70, v35
	v_sub_f32_e32 v69, v69, v35
	v_sub_f32_e32 v68, v68, v35
	v_sub_f32_e32 v67, v67, v35
	v_sub_f32_e32 v66, v66, v35
	v_pk_mul_f32 v[130:131], v[130:131], v[34:35] op_sel_hi:[1,0]
	s_waitcnt lgkmcnt(2)
	v_pk_mul_f32 v[32:33], v[32:33], v[42:43]
	v_pk_mul_f32 v[28:29], v[28:29], v[38:39]
	s_waitcnt lgkmcnt(0)
	v_pk_mul_f32 v[24:25], v[24:25], v[86:87]
	v_pk_mul_f32 v[20:21], v[20:21], v[46:47]
	v_pk_mul_f32 v[30:31], v[30:31], v[40:41]
	v_pk_mul_f32 v[26:27], v[26:27], v[36:37]
	v_pk_mul_f32 v[22:23], v[22:23], v[84:85]
	v_pk_mul_f32 v[18:19], v[18:19], v[44:45]
	v_pk_mul_f32 v[16:17], v[16:17], v[42:43]
	v_pk_mul_f32 v[12:13], v[12:13], v[38:39]
	v_pk_mul_f32 v[8:9], v[8:9], v[86:87]
	v_pk_mul_f32 v[4:5], v[4:5], v[46:47]
	v_pk_mul_f32 v[14:15], v[14:15], v[40:41]
	v_pk_mul_f32 v[10:11], v[10:11], v[36:37]
	v_pk_mul_f32 v[6:7], v[6:7], v[84:85]
	v_pk_mul_f32 v[2:3], v[2:3], v[44:45]
	v_mov_b32_e32 v84, v82
	v_mov_b32_e32 v85, v82
	v_mov_b32_e32 v86, v82
	v_mov_b32_e32 v87, v82
	v_mov_b32_e32 v88, v82
	v_mov_b32_e32 v89, v82
	v_mov_b32_e32 v90, v82
	v_mov_b32_e32 v91, v82
	v_mov_b32_e32 v92, v82
	v_mov_b32_e32 v93, v82
	v_mov_b32_e32 v94, v82
	v_mov_b32_e32 v95, v82
	v_mov_b32_e32 v96, v82
	v_mov_b32_e32 v97, v82
	v_mov_b64_e32 v[34:35], v[82:83]
	v_mov_b32_e32 v112, v82
	v_mov_b32_e32 v111, v82
	v_mov_b32_e32 v110, v82
	v_mov_b32_e32 v109, v82
	v_mov_b32_e32 v108, v82
	v_mov_b32_e32 v107, v82
	v_mov_b32_e32 v106, v82
	v_mov_b32_e32 v105, v82
	v_mov_b32_e32 v104, v82
	v_mov_b32_e32 v103, v82
	v_mov_b32_e32 v102, v82
	v_mov_b32_e32 v101, v82
	v_mov_b32_e32 v100, v82
	v_mov_b32_e32 v99, v82
	v_mov_b32_e32 v98, v82
	v_mov_b64_e32 v[36:37], v[84:85]
	v_mov_b64_e32 v[38:39], v[86:87]
	v_mov_b64_e32 v[40:41], v[88:89]
	v_mov_b64_e32 v[42:43], v[90:91]
	v_mov_b64_e32 v[44:45], v[92:93]
	v_mov_b64_e32 v[46:47], v[94:95]
	v_mov_b64_e32 v[48:49], v[96:97]
	s_branch .Lmla_A0
